# P1: odd XCDs (blockIdx bit 0) start the input-projection GEMM 13 us later than even XCDs, so the epilogue store bursts of the two halves do not coincide
# speedup vs baseline: 1.0078x; 1.0028x over previous
.LBB0_255:
	s_or_b64 exec, exec, s[4:5]
	s_cmpk_lt_i32 s97, 0xc00
	v_mov_b32_e32 v8, v234
	s_cselect_b64 s[4:5], -1, 0
	s_cmpk_gt_i32 s97, 0xbff
	s_waitcnt lgkmcnt(0)
	s_barrier
	s_bfe_u32 s99, s97, 0x10000
	s_cmp_eq_u32 s99, 0
	s_cbranch_scc1 .Lmy_p1_nodelay
	s_mul_i32 s99, s99, 1300
	s_memrealtime s[100:101]
	s_waitcnt lgkmcnt(0)
	s_add_u32 s98, s100, s99
.Lmy_p1_spin:
	s_memrealtime s[100:101]
	s_waitcnt lgkmcnt(0)
	s_sub_u32 s99, s100, s98
	s_cmp_lt_i32 s99, 0
	s_cbranch_scc1 .Lmy_p1_spin
.Lmy_p1_nodelay:
	s_cmpk_gt_i32 s97, 0xbff
	s_cbranch_scc1 .LBB0_257
	s_ashr_i32 s2, s97, 31
	s_lshr_b32 s2, s2, 29
	s_add_i32 s2, s97, s2
	s_ashr_i32 s3, s2, 3
	s_and_b32 s2, s2, -8
	s_sub_i32 s2, s97, s2
	s_cmp_lt_i32 s2, 0
	s_movk_i32 s6, 0x181
	s_cselect_b32 s6, s6, 0x180
	s_mul_i32 s2, s2, s6
	s_add_i32 s2, s2, s3
	s_mul_hi_i32 s3, s2, 0x2aaaaaab
	s_lshr_b32 s6, s3, 31
	s_ashr_i32 s3, s3, 5
	s_add_i32 s3, s3, s6
	s_lshl_b32 s6, s3, 3
	s_mulk_i32 s3, 0xc0
	s_sub_i32 s2, s2, s3
	s_sext_i32_i16 s3, s2
	s_bfe_u32 s3, s3, 0x3001c
	s_add_i32 s3, s2, s3
	s_sext_i32_i16 s7, s3
	s_and_b32 s3, s3, 0xfff8
	s_sub_i32 s2, s2, s3
	s_sext_i32_i16 s2, s2
	s_add_i32 s52, s6, s2
	s_ashr_i32 s46, s7, 3

	.amdhsa_kernel _Z10hybrid_fwd4Args
		.amdhsa_group_segment_fixed_size 0
		.amdhsa_private_segment_fixed_size 0
		.amdhsa_kernarg_size 472
		.amdhsa_user_sgpr_count 2
		.amdhsa_user_sgpr_dispatch_ptr 0
		.amdhsa_user_sgpr_queue_ptr 0
		.amdhsa_user_sgpr_kernarg_segment_ptr 1
		.amdhsa_user_sgpr_dispatch_id 0
		.amdhsa_user_sgpr_kernarg_preload_length 0
		.amdhsa_user_sgpr_kernarg_preload_offset 0
		.amdhsa_user_sgpr_private_segment_size 0
		.amdhsa_uses_dynamic_stack 0
		.amdhsa_enable_private_segment 0
		.amdhsa_system_sgpr_workgroup_id_x 1
		.amdhsa_system_sgpr_workgroup_id_y 0
		.amdhsa_system_sgpr_workgroup_id_z 0
		.amdhsa_system_sgpr_workgroup_info 0
		.amdhsa_system_vgpr_workitem_id 2
		.amdhsa_next_free_vgpr 254
		.amdhsa_next_free_sgpr 102
		.amdhsa_accum_offset 256
		.amdhsa_reserve_vcc 1
		.amdhsa_float_round_mode_32 0
		.amdhsa_float_round_mode_16_64 0
		.amdhsa_float_denorm_mode_32 3
		.amdhsa_float_denorm_mode_16_64 3
		.amdhsa_dx10_clamp 1
		.amdhsa_ieee_mode 1
		.amdhsa_fp16_overflow 0
		.amdhsa_tg_split 0
		.amdhsa_exception_fp_ieee_invalid_op 0
		.amdhsa_exception_fp_denorm_src 0
		.amdhsa_exception_fp_ieee_div_zero 0
		.amdhsa_exception_fp_ieee_overflow 0
		.amdhsa_exception_fp_ieee_underflow 0
		.amdhsa_exception_fp_ieee_inexact 0
		.amdhsa_exception_int_div_zero 0
	.end_amdhsa_kernel

.Lfunc_end0:
	.size	_Z10hybrid_fwd4Args, .Lfunc_end0-_Z10hybrid_fwd4Args
	.set _Z10hybrid_fwd4Args.num_vgpr, 254
	.set _Z10hybrid_fwd4Args.num_agpr, 0
	.set _Z10hybrid_fwd4Args.numbered_sgpr, 102
	.set _Z10hybrid_fwd4Args.num_named_barrier, 0
	.set _Z10hybrid_fwd4Args.private_seg_size, 0
	.set _Z10hybrid_fwd4Args.uses_vcc, 1
	.set _Z10hybrid_fwd4Args.uses_flat_scratch, 0
	.set _Z10hybrid_fwd4Args.has_dyn_sized_stack, 0
	.set _Z10hybrid_fwd4Args.has_recursion, 0
	.set _Z10hybrid_fwd4Args.has_indirect_call, 0

amdhsa.kernels:
  - .agpr_count:     0
    .args:
      - .offset:         0
        .size:           216
        .value_kind:     by_value
      - .offset:         216
        .size:           4
        .value_kind:     hidden_block_count_x
      - .offset:         220
        .size:           4
        .value_kind:     hidden_block_count_y
      - .offset:         224
        .size:           4
        .value_kind:     hidden_block_count_z
      - .offset:         228
        .size:           2
        .value_kind:     hidden_group_size_x
      - .offset:         230
        .size:           2
        .value_kind:     hidden_group_size_y
      - .offset:         232
        .size:           2
        .value_kind:     hidden_group_size_z
      - .offset:         234
        .size:           2
        .value_kind:     hidden_remainder_x
      - .offset:         236
        .size:           2
        .value_kind:     hidden_remainder_y
      - .offset:         238
        .size:           2
        .value_kind:     hidden_remainder_z
      - .offset:         256
        .size:           8
        .value_kind:     hidden_global_offset_x
      - .offset:         264
        .size:           8
        .value_kind:     hidden_global_offset_y
      - .offset:         272
        .size:           8
        .value_kind:     hidden_global_offset_z
      - .offset:         280
        .size:           2
        .value_kind:     hidden_grid_dims
      - .offset:         304
        .size:           8
        .value_kind:     hidden_multigrid_sync_arg
      - .offset:         336
        .size:           4
        .value_kind:     hidden_dynamic_lds_size
    .group_segment_fixed_size: 0
    .kernarg_segment_align: 8
    .kernarg_segment_size: 472
    .language:       OpenCL C
    .language_version:
      - 2
      - 0
    .max_flat_workgroup_size: 512
    .name:           _Z10hybrid_fwd4Args
    .private_segment_fixed_size: 0
    .sgpr_count:     108
    .sgpr_spill_count: 71
    .symbol:         _Z10hybrid_fwd4Args.kd
    .uniform_work_group_size: 1
    .uses_dynamic_stack: false
    .vgpr_count:     254
    .vgpr_spill_count: 0
    .wavefront_size: 64
